# pooling phase: table and halo loads batched, MFMA operands exchanged for 8-byte output stores
# speedup vs baseline: 1.0516x; 1.0038x over previous
; #define INP(i) (p.in[opq(i)])
; __device__ __forceinline__ unsigned f2bf(float f) { unsigned u = __float_as_uint(f); return (u + 0x7fffu + ((u >> 16) & 1u)) >> 16; }
; __device__ __forceinline__ void pool_phase(const Params& p, int layer, LAS unsigned char* lds, int tid) {
;     ...
;     const float* mix = INP(22) + (size_t)layer * 4 * 64 * 64;
;     const float* scale = INP(23) + layer * 256;
;     const int wave = tid >> 6, lane = tid & 63, l15 = lane & 15, quad = lane >> 4;
;     __syncthreads();
;     for (int i = 0; i < 32; ++i) { const int idx = tid + 512 * i, g = idx >> 12, c = (idx >> 6) & 63, d = idx & 63; MT[(g * 64 + d) * 72 + c] = (bf16)f2bf(mix[idx] * scale[g * 64 + d]); }
.LBB0_48:
	s_and_b64 vcc, exec, s[8:9]
	s_cbranch_vccz .LBB0_211
	v_readlane_b32 s0, v247, 57
	s_cmp_eq_u32 s0, 6
	s_mov_b64 s[70:71], -1
	s_cbranch_scc0 .LBB0_211
	v_readlane_b32 s0, v247, 53
	v_mov_b32_e32 v0, v188
	s_mov_b32 s8, 22
	v_readlane_b32 s1, v247, 54
	s_ashr_i32 s9, s8, 31
	s_lshl_b64 s[0:1], s[0:1], 16
	s_lshl_b64 s[8:9], s[8:9], 3
	v_readlane_b32 s10, v247, 46
	v_readlane_b32 s11, v247, 47
	s_add_u32 s8, s10, s8
	s_addc_u32 s9, s11, s9
	s_load_dwordx2 s[8:9], s[8:9], 0x0
	v_ashrrev_i32_e32 v1, 31, v0
	v_ashrrev_i32_e32 v3, 6, v0
	s_movk_i32 s2, 0x90
	s_movk_i32 s4, 0x90
	s_waitcnt lgkmcnt(0)
	s_add_u32 s0, s8, s0
	s_mov_b32 s8, 23
	s_addc_u32 s1, s9, s1
	s_ashr_i32 s9, s8, 31
	s_lshl_b64 s[8:9], s[8:9], 3
	s_add_u32 s8, s10, s8
	s_addc_u32 s9, s11, s9
	s_load_dwordx2 s[10:11], s[8:9], 0x0
	s_lshl_b64 s[8:9], s[56:57], 2
	s_waitcnt vmcnt(0)
	v_lshl_add_u64 v[4:5], v[0:1], 2, s[0:1]
	s_movk_i32 s1, 0xffc0
	v_bfi_b32 v6, s1, v3, v0
	s_waitcnt lgkmcnt(0)
	s_add_u32 s12, s10, s8
	s_addc_u32 s13, s11, s9
	v_ashrrev_i32_e32 v7, 31, v6
	v_lshl_add_u64 v[8:9], v[6:7], 2, s[12:13]
	s_barrier
	v_and_b32_e32 v6, 63, v0
	v_lshlrev_b32_e32 v7, 2, v6
	v_add_co_u32_e32 v10, vcc, 0x1000, v4
	global_load_dword v49, v7, s[12:13]
	global_load_dword v50, v7, s[12:13] offset:256
	v_addc_co_u32_e32 v11, vcc, 0, v5, vcc
	global_load_dword v51, v7, s[12:13] offset:512
	global_load_dword v52, v7, s[12:13] offset:768
	global_load_dword v17, v[10:11], off offset:-4096
	global_load_dword v18, v[10:11], off offset:-2048
	global_load_dword v19, v[10:11], off
	global_load_dword v20, v[10:11], off offset:2048
	v_add_co_u32_e32 v10, vcc, 0x2000, v10
	s_nop 1
	v_addc_co_u32_e32 v11, vcc, 0, v11, vcc
	global_load_dword v21, v[10:11], off offset:-4096
	global_load_dword v22, v[10:11], off offset:-2048
	global_load_dword v23, v[10:11], off
	global_load_dword v24, v[10:11], off offset:2048
	v_add_co_u32_e32 v10, vcc, 0x2000, v10
	s_nop 1
	v_addc_co_u32_e32 v11, vcc, 0, v11, vcc
	global_load_dword v25, v[10:11], off offset:-4096
	global_load_dword v26, v[10:11], off offset:-2048
	global_load_dword v27, v[10:11], off
	global_load_dword v28, v[10:11], off offset:2048
	v_add_co_u32_e32 v10, vcc, 0x2000, v10
	s_nop 1
	v_addc_co_u32_e32 v11, vcc, 0, v11, vcc
	global_load_dword v29, v[10:11], off offset:-4096
	global_load_dword v30, v[10:11], off offset:-2048
	global_load_dword v31, v[10:11], off
	global_load_dword v32, v[10:11], off offset:2048
	v_add_co_u32_e32 v10, vcc, 0x2000, v10
	s_nop 1
	v_addc_co_u32_e32 v11, vcc, 0, v11, vcc
	global_load_dword v33, v[10:11], off offset:-4096
	global_load_dword v34, v[10:11], off offset:-2048
	global_load_dword v35, v[10:11], off
	global_load_dword v36, v[10:11], off offset:2048
	v_add_co_u32_e32 v10, vcc, 0x2000, v10
	s_nop 1
	v_addc_co_u32_e32 v11, vcc, 0, v11, vcc
	global_load_dword v37, v[10:11], off offset:-4096
	global_load_dword v38, v[10:11], off offset:-2048
	global_load_dword v39, v[10:11], off
	global_load_dword v40, v[10:11], off offset:2048
	v_add_co_u32_e32 v10, vcc, 0x2000, v10
	s_nop 1
	v_addc_co_u32_e32 v11, vcc, 0, v11, vcc
	global_load_dword v41, v[10:11], off offset:-4096
	global_load_dword v42, v[10:11], off offset:-2048
	global_load_dword v43, v[10:11], off
	global_load_dword v44, v[10:11], off offset:2048
	v_add_co_u32_e32 v10, vcc, 0x2000, v10
	s_nop 1
	v_addc_co_u32_e32 v11, vcc, 0, v11, vcc
	global_load_dword v45, v[10:11], off offset:-4096
	global_load_dword v46, v[10:11], off offset:-2048
	global_load_dword v47, v[10:11], off
	global_load_dword v48, v[10:11], off offset:2048
	v_mul_u32_u24_e32 v8, 0x90, v6
	v_lshrrev_b32_e32 v9, 5, v0
	v_and_b32_e32 v9, 14, v9
	v_add_u32_e32 v8, v8, v9
	s_waitcnt vmcnt(24)
	v_mul_f32_e32 v53, v17, v49
	v_bfe_u32 v54, v53, 16, 1
	v_add3_u32 v53, v53, v54, s88
	ds_write_b16_d16_hi v8, v53 offset:65024
	v_mul_f32_e32 v55, v18, v49
	v_bfe_u32 v56, v55, 16, 1
	v_add3_u32 v55, v55, v56, s88
	ds_write_b16_d16_hi v8, v55 offset:65040
	v_mul_f32_e32 v57, v19, v49
	v_bfe_u32 v58, v57, 16, 1
	v_add3_u32 v57, v57, v58, s88
	ds_write_b16_d16_hi v8, v57 offset:65056
	v_mul_f32_e32 v59, v20, v49
	v_bfe_u32 v60, v59, 16, 1
	v_add3_u32 v59, v59, v60, s88
	ds_write_b16_d16_hi v8, v59 offset:65072
	v_mul_f32_e32 v53, v21, v49
	v_bfe_u32 v54, v53, 16, 1
	v_add3_u32 v53, v53, v54, s88
	ds_write_b16_d16_hi v8, v53 offset:65088
	v_mul_f32_e32 v55, v22, v49
	v_bfe_u32 v56, v55, 16, 1
	v_add3_u32 v55, v55, v56, s88
	ds_write_b16_d16_hi v8, v55 offset:65104
	v_mul_f32_e32 v57, v23, v49
	v_bfe_u32 v58, v57, 16, 1
	v_add3_u32 v57, v57, v58, s88
	ds_write_b16_d16_hi v8, v57 offset:65120
	v_mul_f32_e32 v59, v24, v49
	v_bfe_u32 v60, v59, 16, 1
	v_add3_u32 v59, v59, v60, s88
	ds_write_b16_d16_hi v8, v59 offset:65136
	v_add_u32_e32 v8, 0x2400, v8
	s_waitcnt vmcnt(16)
	v_mul_f32_e32 v53, v25, v50
	v_bfe_u32 v54, v53, 16, 1
	v_add3_u32 v53, v53, v54, s88
	ds_write_b16_d16_hi v8, v53 offset:65024
	v_mul_f32_e32 v55, v26, v50
	v_bfe_u32 v56, v55, 16, 1
	v_add3_u32 v55, v55, v56, s88
	ds_write_b16_d16_hi v8, v55 offset:65040
	v_mul_f32_e32 v57, v27, v50
	v_bfe_u32 v58, v57, 16, 1
	v_add3_u32 v57, v57, v58, s88
	ds_write_b16_d16_hi v8, v57 offset:65056
	v_mul_f32_e32 v59, v28, v50
	v_bfe_u32 v60, v59, 16, 1
	v_add3_u32 v59, v59, v60, s88
	ds_write_b16_d16_hi v8, v59 offset:65072
	v_mul_f32_e32 v53, v29, v50
	v_bfe_u32 v54, v53, 16, 1
	v_add3_u32 v53, v53, v54, s88
	ds_write_b16_d16_hi v8, v53 offset:65088
	v_mul_f32_e32 v55, v30, v50
	v_bfe_u32 v56, v55, 16, 1
	v_add3_u32 v55, v55, v56, s88
	ds_write_b16_d16_hi v8, v55 offset:65104
	v_mul_f32_e32 v57, v31, v50
	v_bfe_u32 v58, v57, 16, 1
	v_add3_u32 v57, v57, v58, s88
	ds_write_b16_d16_hi v8, v57 offset:65120
	v_mul_f32_e32 v59, v32, v50
	v_bfe_u32 v60, v59, 16, 1
	v_add3_u32 v59, v59, v60, s88
	ds_write_b16_d16_hi v8, v59 offset:65136
	v_add_u32_e32 v8, 0x2400, v8
	s_waitcnt vmcnt(8)
; __device__ __forceinline__ unsigned f2bf(float f) { unsigned u = __float_as_uint(f); return (u + 0x7fffu + ((u >> 16) & 1u)) >> 16; }
; __device__ __forceinline__ void pool_phase(const Params& p, int layer, LAS unsigned char* lds, int tid) {
;     ...
;     for (int i = 0; i < 32; ++i) { const int idx = tid + 512 * i, g = idx >> 12, c = (idx >> 6) & 63, d = idx & 63; MT[(g * 64 + d) * 72 + c] = (bf16)f2bf(mix[idx] * scale[g * 64 + d]); }
	v_mul_f32_e32 v53, v33, v51
	v_bfe_u32 v54, v53, 16, 1
	v_add3_u32 v53, v53, v54, s88
	ds_write_b16_d16_hi v8, v53 offset:65024
	v_mul_f32_e32 v55, v34, v51
	v_bfe_u32 v56, v55, 16, 1
	v_add3_u32 v55, v55, v56, s88
	ds_write_b16_d16_hi v8, v55 offset:65040
	v_mul_f32_e32 v57, v35, v51
	v_bfe_u32 v58, v57, 16, 1
	v_add3_u32 v57, v57, v58, s88
	ds_write_b16_d16_hi v8, v57 offset:65056
	v_mul_f32_e32 v59, v36, v51
	v_bfe_u32 v60, v59, 16, 1
	v_add3_u32 v59, v59, v60, s88
	ds_write_b16_d16_hi v8, v59 offset:65072
	v_mul_f32_e32 v53, v37, v51
	v_bfe_u32 v54, v53, 16, 1
	v_add3_u32 v53, v53, v54, s88
	ds_write_b16_d16_hi v8, v53 offset:65088
	v_mul_f32_e32 v55, v38, v51
	v_bfe_u32 v56, v55, 16, 1
	v_add3_u32 v55, v55, v56, s88
	ds_write_b16_d16_hi v8, v55 offset:65104
	v_mul_f32_e32 v57, v39, v51
	v_bfe_u32 v58, v57, 16, 1
	v_add3_u32 v57, v57, v58, s88
	ds_write_b16_d16_hi v8, v57 offset:65120
	v_mul_f32_e32 v59, v40, v51
	v_bfe_u32 v60, v59, 16, 1
	v_add3_u32 v59, v59, v60, s88
	ds_write_b16_d16_hi v8, v59 offset:65136
	v_add_u32_e32 v8, 0x2400, v8
	s_waitcnt vmcnt(0)
	v_mul_f32_e32 v53, v41, v52
	v_bfe_u32 v54, v53, 16, 1
	v_add3_u32 v53, v53, v54, s88
	ds_write_b16_d16_hi v8, v53 offset:65024
	v_mul_f32_e32 v55, v42, v52
	v_bfe_u32 v56, v55, 16, 1
	v_add3_u32 v55, v55, v56, s88
	ds_write_b16_d16_hi v8, v55 offset:65040
	v_mul_f32_e32 v57, v43, v52
	v_bfe_u32 v58, v57, 16, 1
	v_add3_u32 v57, v57, v58, s88
	ds_write_b16_d16_hi v8, v57 offset:65056
	v_mul_f32_e32 v59, v44, v52
	v_bfe_u32 v60, v59, 16, 1
	v_add3_u32 v59, v59, v60, s88
	ds_write_b16_d16_hi v8, v59 offset:65072
	v_mul_f32_e32 v53, v45, v52
	v_bfe_u32 v54, v53, 16, 1
	v_add3_u32 v53, v53, v54, s88
	ds_write_b16_d16_hi v8, v53 offset:65088
	v_mul_f32_e32 v55, v46, v52
	v_bfe_u32 v56, v55, 16, 1
	v_add3_u32 v55, v55, v56, s88
	ds_write_b16_d16_hi v8, v55 offset:65104
	v_mul_f32_e32 v57, v47, v52
	v_bfe_u32 v58, v57, 16, 1
	v_add3_u32 v57, v57, v58, s88
	ds_write_b16_d16_hi v8, v57 offset:65120
	v_mul_f32_e32 v59, v48, v52
	v_bfe_u32 v60, v59, 16, 1
	v_add3_u32 v59, v59, v60, s88
	ds_write_b16_d16_hi v8, v59 offset:65136
	v_add_u32_e32 v1, 0x200, v0
	v_add_u32_e32 v3, 0x400, v0
	v_readlane_b32 s0, v248, 3
	v_readlane_b32 s1, v248, 4
	s_nop 0
	s_andn2_b64 vcc, exec, s[0:1]
	s_cbranch_vccnz .LBB0_195
; #define LAS __attribute__((address_space(3)))
; __device__ __forceinline__ float bflo(unsigned w) { return __uint_as_float(w << 16); }
; __device__ __forceinline__ float bfhi(unsigned w) { return __uint_as_float(w & 0xffff0000u); }
; __device__ __forceinline__ unsigned f2bf(float f) { unsigned u = __float_as_uint(f); return (u + 0x7fffu + ((u >> 16) & 1u)) >> 16; }
; __device__ __forceinline__ void pool_phase(const Params& p, int layer, LAS unsigned char* lds, int tid) {
;     ...
;         const int m0 = tile * 32;
;         __syncthreads();
; #pragma unroll
;         for (int i = 0; i < 3; ++i) { const int idx = tid + i * 512;
;             if (idx < 47 * 32) { const int r = idx >> 5, ch = idx & 31, mm = m0 - 15 + r;
;                 u32x4 w = (u32x4){0, 0, 0, 0};
;                 if (mm >= 0) w = *(const u32x4*)(PROJ + (size_t)mm * PC + 1024 + ch * 8);
;                 LAS float* d = U + r * 256 + ch * 8;
;                 *(LAS f32x4*)d = (f32x4){bflo(w.x), bfhi(w.x), bflo(w.y), bfhi(w.y)}; *(LAS f32x4*)(d + 4) = (f32x4){bflo(w.z), bfhi(w.z), bflo(w.w), bfhi(w.w)}; } }
;         __syncthreads();
;         {
;             const int c = tid & 255, rb = (tid >> 8) * 16, g = c >> 6, w = 2 << g; const float invw = 1.0f / (float)w;
;             float sum = 0.f;
;             for (int j = 0; j < w; ++j) sum += U[(15 + rb - j) * 256 + c];
;             int t = (m0 + rb) % L;
;             for (int i = 0; i < 16; ++i) {
;                 const int r = rb + i; const float cur = U[(15 + r) * 256 + c];
;                 if (i > 0) sum += cur - U[(15 + r - w) * 256 + c];
;                 float pv;
;                 if (t + 1 >= w) pv = sum * invw - cur;
;                 else { float s2 = 0.f; for (int j = 0; j <= t; ++j) s2 += U[(15 + r - j) * 256 + c]; pv = s2 / (float)(t + 1) - cur; }
;                 PB[r * 264 + c] = (bf16)f2bf(pv);
;                 t = (t + 1 == L) ? 0 : t + 1;
;             }
;         }
;         __syncthreads();
;         {
;             const int g = wave >> 1, mt = wave & 1;
;             bf16x8 a[2];
; #pragma unroll
;             for (int ks = 0; ks < 2; ++ks) a[ks] = *(const LAS bf16x8*)(PB + (mt * 16 + l15) * 264 + g * 64 + ks * 32 + quad * 8);
	v_and_b32_e32 v7, 31, v0
	v_ashrrev_i32_e32 v9, 4, v0
	v_lshlrev_b32_e32 v12, 3, v7
	v_lshl_add_u32 v8, v7, 5, 0
	v_and_b32_e32 v13, -16, v9
	v_bfe_u32 v7, v0, 6, 2
	v_lshlrev_b32_e64 v16, v7, 2
	v_add_u32_e32 v24, 17, v13
	v_lshlrev_b32_e32 v46, 10, v24
	v_sub_u32_e32 v24, v24, v16
	v_lshlrev_b32_e32 v47, 10, v24
	v_add_u32_e32 v24, 18, v13
	v_lshlrev_b32_e32 v48, 10, v24
	v_sub_u32_e32 v24, v24, v16
	v_lshlrev_b32_e32 v49, 10, v24
	v_add_u32_e32 v24, 19, v13
	v_lshlrev_b32_e32 v50, 10, v24
	v_sub_u32_e32 v24, v24, v16
	v_lshlrev_b32_e32 v51, 10, v24
	v_add_u32_e32 v24, 20, v13
	v_lshlrev_b32_e32 v52, 10, v24
	v_sub_u32_e32 v24, v24, v16
	v_lshlrev_b32_e32 v53, 10, v24
	v_add_u32_e32 v24, 21, v13
	v_lshlrev_b32_e32 v54, 10, v24
	v_sub_u32_e32 v24, v24, v16
	v_lshlrev_b32_e32 v55, 10, v24
	v_add_u32_e32 v24, 22, v13
	v_lshlrev_b32_e32 v56, 10, v24
	v_sub_u32_e32 v24, v24, v16
	v_lshlrev_b32_e32 v57, 10, v24
	v_add_u32_e32 v24, 23, v13
	v_lshlrev_b32_e32 v58, 10, v24
	v_sub_u32_e32 v24, v24, v16
	v_lshrrev_b32_e32 v4, 6, v0
	v_lshl_add_u32 v7, v7, 23, v175
	v_lshlrev_b32_sdwa v11, v176, v0 dst_sel:DWORD dst_unused:UNUSED_PAD src0_sel:DWORD src1_sel:BYTE_0
	v_lshlrev_b32_e32 v59, 10, v24
	v_add_u32_e32 v24, 24, v13
	v_xor_b32_e32 v17, 1.0, v7
	v_add_u32_e32 v18, 0, v11
	v_lshlrev_b32_sdwa v7, v174, v0 dst_sel:DWORD dst_unused:UNUSED_PAD src0_sel:DWORD src1_sel:BYTE_0
	v_lshlrev_b32_e32 v4, 4, v4
	v_lshlrev_b32_e32 v60, 10, v24
	v_sub_u32_e32 v24, v24, v16
	v_and_b32_e32 v6, 15, v0
	v_sub_u32_e32 v76, v18, v7
	v_and_b32_e32 v7, 16, v4
	v_lshlrev_b32_e32 v61, 10, v24
	v_add_u32_e32 v24, 25, v13
	v_or_b32_e32 v4, v7, v6
	v_lshlrev_b32_e32 v62, 10, v24
	v_sub_u32_e32 v24, v24, v16
	v_mul_u32_u24_e32 v4, 0x210, v4
	v_and_b32_e32 v14, 0xffffff80, v0
	v_lshlrev_b32_e32 v63, 10, v24
	v_add_u32_e32 v24, 26, v13
	v_add3_u32 v75, 0, v4, v14
	v_ashrrev_i32_e32 v4, 1, v0
	v_lshlrev_b32_e32 v64, 10, v24
	v_sub_u32_e32 v24, v24, v16
	v_bfe_u32 v5, v0, 4, 2
	v_and_b32_e32 v4, 0xffffffc0, v4
	v_readlane_b32 s0, v248, 5
	v_lshlrev_b32_e32 v65, 10, v24
	v_add_u32_e32 v24, 27, v13
	v_lshlrev_b32_e32 v77, 4, v5
	v_lshl_or_b32 v19, v5, 2, v7
	v_ashrrev_i32_e32 v5, 31, v4
	v_readlane_b32 s1, v248, 6
	v_lshlrev_b32_e32 v66, 10, v24
	v_sub_u32_e32 v24, v24, v16
	v_or_b32_e32 v23, v4, v6
	v_lshl_add_u64 v[4:5], v[4:5], 1, s[0:1]
	s_movk_i32 s0, 0x5e0
	v_lshlrev_b32_e32 v67, 10, v24
	v_add_u32_e32 v24, 28, v13
	v_cmp_gt_i32_e64 s[38:39], s0, v0
	s_movk_i32 s0, 0x3e0
	v_lshlrev_b32_e32 v68, 10, v24
	v_sub_u32_e32 v24, v24, v16
	v_cmp_gt_i32_e64 s[40:41], s0, v0
	s_movk_i32 s0, 0x1e0
	v_lshlrev_b32_e32 v69, 10, v24
	v_add_u32_e32 v24, 29, v13
	v_or_b32_e32 v10, 15, v9
	v_lshlrev_b32_e32 v6, 1, v6
	v_mov_b32_e32 v7, v2
	v_cmp_gt_i32_e64 s[42:43], s0, v0
	s_movk_i32 s0, 0x210
	v_lshlrev_b32_e32 v70, 10, v24
	v_sub_u32_e32 v24, v24, v16
	v_lshl_add_u64 v[14:15], v[4:5], 0, v[6:7]
	v_lshlrev_b32_e32 v22, 10, v10
	v_mul_lo_u32 v5, v13, s0
	v_lshlrev_b32_e32 v71, 10, v24
	v_add_u32_e32 v24, 15, v10
	v_mul_lo_u32 v10, v10, s0
	v_lshlrev_b32_e32 v9, 10, v9
	s_movk_i32 s0, 0xc000
	v_and_or_b32 v9, v9, s0, v11
	s_add_i32 s0, 0, 0x4000
	v_add_u32_e32 v26, s0, v9
	v_readlane_b32 s0, v247, 32
	v_add_u32_e32 v6, 16, v13
	v_ashrrev_i32_e32 v20, 5, v0
	v_add_u32_e32 v27, s0, v9
	v_readlane_b32 s0, v247, 33
	v_ashrrev_i32_e32 v21, 5, v1
	v_ashrrev_i32_e32 v3, 5, v3
	v_add_u32_e32 v28, s0, v9
	v_readlane_b32 s0, v247, 34
	v_lshlrev_b32_e32 v7, 10, v6
	v_sub_u32_e32 v6, v6, v16
	v_add_u32_e32 v29, s0, v9
	s_add_i32 s0, 0, 0x5000
	v_add_u32_e32 v30, s0, v9
	v_readlane_b32 s0, v247, 35
	v_lshlrev_b32_e32 v72, 10, v24
	v_sub_u32_e32 v24, v24, v16
	v_add_u32_e32 v31, s0, v9
	v_readlane_b32 s0, v247, 36
	v_mul_lo_u32 v23, v23, s4
	v_lshlrev_b32_e32 v4, 10, v20
	v_add_u32_e32 v32, s0, v9
	v_readlane_b32 s0, v247, 37
	v_lshlrev_b32_e32 v1, 10, v21
	v_lshlrev_b32_e32 v0, 10, v3
	v_add_u32_e32 v33, s0, v9
	s_add_i32 s0, 0, 0x6000
	v_add_u32_e32 v34, s0, v9
	v_readlane_b32 s0, v247, 38
	v_lshlrev_b32_e32 v6, 10, v6
	v_lshlrev_b32_e32 v73, 10, v24
	v_add_u32_e32 v35, s0, v9
	v_readlane_b32 s0, v247, 39
	v_add3_u32 v23, 0, v77, v23
	v_or_b32_e32 v40, v22, v11
	v_add_u32_e32 v36, s0, v9
	v_readlane_b32 s0, v247, 40
	v_add_u32_e32 v24, 0xfe00, v23
	v_add_u32_e32 v25, 0, v40
	v_add_u32_e32 v37, s0, v9
	s_add_i32 s0, 0, 0x7000
	v_add_u32_e32 v38, s0, v9
	v_readlane_b32 s0, v247, 41
	v_add_u32_e32 v41, v8, v4
	v_add_u32_e32 v42, v8, v1
	v_add_u32_e32 v39, s0, v9
	s_add_i32 s0, 0, 0x3c00
	v_add_u32_e32 v40, s0, v40
	v_add_u32_e32 v43, v8, v0
	v_add_u32_e32 v44, v18, v7
	v_add_u32_e32 v45, v18, v6
	v_add_u32_e32 v46, v18, v46
	v_add_u32_e32 v47, v18, v47
	v_add_u32_e32 v48, v18, v48
	v_add_u32_e32 v49, v18, v49
	v_add_u32_e32 v50, v18, v50
	v_add_u32_e32 v51, v18, v51
	v_add_u32_e32 v52, v18, v52
	v_add_u32_e32 v53, v18, v53
	v_add_u32_e32 v54, v18, v54
	v_add_u32_e32 v55, v18, v55
	v_add_u32_e32 v56, v18, v56
	v_add_u32_e32 v57, v18, v57
	v_add_u32_e32 v58, v18, v58
	v_add_u32_e32 v59, v18, v59
	v_add_u32_e32 v60, v18, v60
	v_add_u32_e32 v61, v18, v61
	v_add_u32_e32 v62, v18, v62
	v_add_u32_e32 v63, v18, v63
	v_add_u32_e32 v64, v18, v64
	v_add_u32_e32 v65, v18, v65
	v_add_u32_e32 v66, v18, v66
	v_add_u32_e32 v67, v18, v67
	v_add_u32_e32 v68, v18, v68
	v_add_u32_e32 v69, v18, v69
	v_add_u32_e32 v70, v18, v70
	v_add_u32_e32 v71, v18, v71
	v_add_u32_e32 v72, v18, v72
	v_add_u32_e32 v73, v18, v73
	v_add_u32_e32 v74, v76, v10
	v_add_u32_e32 v75, v75, v77
	v_add_u32_e32 v76, v76, v5
	s_mov_b32 s0, s64
	s_branch .LBB0_54

; #define LAS __attribute__((address_space(3)))
; __device__ __forceinline__ float bflo(unsigned w) { return __uint_as_float(w << 16); }
; __device__ __forceinline__ float bfhi(unsigned w) { return __uint_as_float(w & 0xffff0000u); }
; __device__ __forceinline__ unsigned f2bf(float f) { unsigned u = __float_as_uint(f); return (u + 0x7fffu + ((u >> 16) & 1u)) >> 16; }
; __device__ __forceinline__ void pool_phase(const Params& p, int layer, LAS unsigned char* lds, int tid) {
;     ...
; #pragma unroll
;         for (int i = 0; i < 3; ++i) { const int idx = tid + i * 512;
;             if (idx < 47 * 32) { const int r = idx >> 5, ch = idx & 31, mm = m0 - 15 + r;
;                 u32x4 w = (u32x4){0, 0, 0, 0};
;                 if (mm >= 0) w = *(const u32x4*)(PROJ + (size_t)mm * PC + 1024 + ch * 8);
;                 LAS float* d = U + r * 256 + ch * 8;
;                 *(LAS f32x4*)d = (f32x4){bflo(w.x), bfhi(w.x), bflo(w.y), bfhi(w.y)}; *(LAS f32x4*)(d + 4) = (f32x4){bflo(w.z), bfhi(w.z), bflo(w.w), bfhi(w.w)}; } }
;     ...
;         {
;             const int g = wave >> 1, mt = wave & 1;
;             bf16x8 a[2];
; #pragma unroll
;             for (int ks = 0; ks < 2; ++ks) a[ks] = *(const LAS bf16x8*)(PB + (mt * 16 + l15) * 264 + g * 64 + ks * 32 + quad * 8);
; #pragma unroll
;             for (int nt = 0; nt < 4; ++nt) {
;                 f32x4 acc = (f32x4){0.f, 0.f, 0.f, 0.f};
; #pragma unroll
;                 for (int ks = 0; ks < 2; ++ks) { const bf16x8 bfr = *(const LAS bf16x8*)(MT + (g * 64 + nt * 16 + l15) * 72 + ks * 32 + quad * 8);
;                     acc = __builtin_amdgcn_mfma_f32_16x16x32_bf16(a[ks], bfr, acc, 0, 0, 0); }
; #pragma unroll
;                 for (int j = 0; j < 4; ++j) YB[(size_t)(m0 + mt * 16 + quad * 4 + j) * 256 + g * 64 + nt * 16 + l15] = (bf16)f2bf(acc[j]);
.LBB0_53:
	s_or_b64 exec, exec, s[10:11]
	s_waitcnt lgkmcnt(0)
	v_sub_f32_e32 v0, v6, v4
	v_bfe_u32 v1, v0, 16, 1
	v_add3_u32 v0, v0, v1, s88
	ds_write_b16_d16_hi v74, v0 offset:48128
	s_waitcnt lgkmcnt(0)
	s_barrier
	ds_read_b128 v[8:11], v75 offset:48128
	ds_read_b128 v[4:7], v75 offset:48192
	ds_read_b128 v[78:81], v23 offset:65024
	ds_read_b128 v[82:85], v23 offset:65088
	v_mbcnt_lo_u32_b32 v92, -1, 0
	v_mbcnt_hi_u32_b32 v92, -1, v92
	v_and_b32_e32 v93, 15, v92
	v_lshrrev_b32_e32 v94, 4, v92
	v_and_b32_e32 v96, 16, v19
	v_or3_b32 v96, v96, v93, s1
	v_mov_b32_e32 v97, 0
	v_lshlrev_b64 v[0:1], 9, v[96:97]
	v_lshl_add_u64 v[0:1], v[14:15], 0, v[0:1]
	v_lshlrev_b32_e32 v94, 3, v94
	v_lshlrev_b32_e32 v93, 1, v93
	v_sub_u32_e32 v94, v94, v93
	v_ashrrev_i32_e32 v95, 31, v94
	v_lshl_add_u64 v[0:1], v[0:1], 0, v[94:95]
	s_mov_b32 s12, 0x07060302
	s_add_i32 s0, s0, s95
	s_waitcnt lgkmcnt(0)
	v_mfma_f32_16x16x32_bf16 v[86:89], v[78:81], v[8:11], 0
	v_mfma_f32_16x16x32_bf16 v[86:89], v[82:85], v[4:7], v[86:89]
	ds_read_b128 v[78:81], v24 offset:2304
	ds_read_b128 v[82:85], v24 offset:2368
	s_nop 7
	s_nop 4
	v_bfe_u32 v97, v86, 16, 1
	v_bfe_u32 v98, v87, 16, 1
	v_bfe_u32 v99, v88, 16, 1
	v_bfe_u32 v100, v89, 16, 1
	v_add3_u32 v86, v86, v97, s88
	v_add3_u32 v87, v87, v98, s88
	v_add3_u32 v88, v88, v99, s88
	v_add3_u32 v89, v89, v100, s88
	v_perm_b32 v90, v87, v86, s12
	v_perm_b32 v91, v89, v88, s12
	global_store_dwordx2 v[0:1], v[90:91], off
	s_waitcnt lgkmcnt(0)
	v_mfma_f32_16x16x32_bf16 v[86:89], v[78:81], v[8:11], 0
	v_mfma_f32_16x16x32_bf16 v[86:89], v[82:85], v[4:7], v[86:89]
	ds_read_b128 v[78:81], v24 offset:4608
	ds_read_b128 v[82:85], v24 offset:4672
	s_nop 7
	s_nop 4
	v_bfe_u32 v97, v86, 16, 1
	v_bfe_u32 v98, v87, 16, 1
	v_bfe_u32 v99, v88, 16, 1
	v_bfe_u32 v100, v89, 16, 1
	v_add3_u32 v86, v86, v97, s88
	v_add3_u32 v87, v87, v98, s88
	v_add3_u32 v88, v88, v99, s88
	v_add3_u32 v89, v89, v100, s88
	v_perm_b32 v90, v87, v86, s12
	v_perm_b32 v91, v89, v88, s12
	global_store_dwordx2 v[0:1], v[90:91], off offset:32
	s_waitcnt lgkmcnt(0)
	v_mfma_f32_16x16x32_bf16 v[86:89], v[78:81], v[8:11], 0
	v_mfma_f32_16x16x32_bf16 v[86:89], v[82:85], v[4:7], v[86:89]
	ds_read_b128 v[78:81], v24 offset:6912
	ds_read_b128 v[82:85], v24 offset:6976
	s_nop 7
	s_nop 4
	v_bfe_u32 v97, v86, 16, 1
	v_bfe_u32 v98, v87, 16, 1
	v_bfe_u32 v99, v88, 16, 1
	v_bfe_u32 v100, v89, 16, 1
	v_add3_u32 v86, v86, v97, s88
	v_add3_u32 v87, v87, v98, s88
	v_add3_u32 v88, v88, v99, s88
	v_add3_u32 v89, v89, v100, s88
	v_perm_b32 v90, v87, v86, s12
	v_perm_b32 v91, v89, v88, s12
	global_store_dwordx2 v[0:1], v[90:91], off offset:64
	s_waitcnt lgkmcnt(0)
	v_mfma_f32_16x16x32_bf16 v[86:89], v[78:81], v[8:11], 0
	v_mfma_f32_16x16x32_bf16 v[86:89], v[82:85], v[4:7], v[86:89]
	s_nop 7
	s_nop 4
	v_bfe_u32 v97, v86, 16, 1
	v_bfe_u32 v98, v87, 16, 1
	v_bfe_u32 v99, v88, 16, 1
	v_bfe_u32 v100, v89, 16, 1
	v_add3_u32 v86, v86, v97, s88
	v_add3_u32 v87, v87, v98, s88
	v_add3_u32 v88, v88, v99, s88
	v_add3_u32 v89, v89, v100, s88
	v_perm_b32 v90, v87, v86, s12
	v_perm_b32 v91, v89, v88, s12
	global_store_dwordx2 v[0:1], v[90:91], off offset:96
	s_cmpk_lt_i32 s0, 0x808
	s_cbranch_scc0 .LBB0_195
.LBB0_54:
	s_lshl_b32 s1, s0, 5
	s_add_i32 s2, s1, -15
	s_waitcnt lgkmcnt(0)
	s_barrier
	s_and_saveexec_b64 s[10:11], s[38:39]
	v_add_u32_e32 v0, s2, v20
	v_cmp_lt_i32_e32 vcc, -1, v0
	v_mov_b32_e32 v92, 0
	v_mov_b32_e32 v93, 0
	v_mov_b32_e32 v94, 0
	v_mov_b32_e32 v95, 0
	s_and_saveexec_b64 s[12:13], vcc
	s_cbranch_execz .Lpool_h0
	v_mov_b64_e32 v[4:5], s[82:83]
	v_mad_u64_u32 v[0:1], s[14:15], v0, s77, v[4:5]
	v_lshlrev_b32_e32 v4, 1, v12
	v_mov_b32_e32 v5, v2
	v_lshl_add_u64 v[0:1], v[0:1], 0, v[4:5]
	v_add_co_u32_e32 v0, vcc, 0x10200000, v0
	s_nop 1
	v_addc_co_u32_e32 v1, vcc, 0, v1, vcc
	global_load_dwordx4 v[92:95], v[0:1], off offset:2048
.Lpool_h0:
	s_or_b64 exec, exec, s[12:13]
	s_or_b64 exec, exec, s[10:11]
	s_and_saveexec_b64 s[10:11], s[40:41]
	v_add_u32_e32 v0, s2, v21
	v_cmp_lt_i32_e32 vcc, -1, v0
	v_mov_b32_e32 v96, 0
	v_mov_b32_e32 v97, 0
	v_mov_b32_e32 v98, 0
	v_mov_b32_e32 v99, 0
	s_and_saveexec_b64 s[12:13], vcc
	s_cbranch_execz .Lpool_h1
	v_mov_b64_e32 v[4:5], s[82:83]
	v_mad_u64_u32 v[0:1], s[14:15], v0, s77, v[4:5]
	v_lshlrev_b32_e32 v4, 1, v12
	v_mov_b32_e32 v5, v2
	v_lshl_add_u64 v[0:1], v[0:1], 0, v[4:5]
	v_add_co_u32_e32 v0, vcc, 0x10200000, v0
	s_nop 1
	v_addc_co_u32_e32 v1, vcc, 0, v1, vcc
	global_load_dwordx4 v[96:99], v[0:1], off offset:2048
.Lpool_h1:
	s_or_b64 exec, exec, s[12:13]
	s_or_b64 exec, exec, s[10:11]
	s_and_saveexec_b64 s[10:11], s[42:43]
	v_add_u32_e32 v0, s2, v3
	v_cmp_lt_i32_e32 vcc, -1, v0
	v_mov_b32_e32 v100, 0
	v_mov_b32_e32 v101, 0
	v_mov_b32_e32 v102, 0
	v_mov_b32_e32 v103, 0
	s_and_saveexec_b64 s[12:13], vcc
	s_cbranch_execz .Lpool_h2
	v_mov_b64_e32 v[4:5], s[82:83]
	v_mad_u64_u32 v[0:1], s[14:15], v0, s77, v[4:5]
	v_lshlrev_b32_e32 v4, 1, v12
	v_mov_b32_e32 v5, v2
	v_lshl_add_u64 v[0:1], v[0:1], 0, v[4:5]
	v_add_co_u32_e32 v0, vcc, 0x10200000, v0
	s_nop 1
	v_addc_co_u32_e32 v1, vcc, 0, v1, vcc
	global_load_dwordx4 v[100:103], v[0:1], off offset:2048
.Lpool_h2:
	s_or_b64 exec, exec, s[12:13]
	s_or_b64 exec, exec, s[10:11]
	s_waitcnt vmcnt(0)
	s_and_saveexec_b64 s[10:11], s[38:39]
	v_lshlrev_b32_e32 v104, 16, v92
	v_and_b32_e32 v105, 0xffff0000, v92
	v_lshlrev_b32_e32 v106, 16, v93
	v_and_b32_e32 v107, 0xffff0000, v93
	v_lshlrev_b32_e32 v108, 16, v94
	v_and_b32_e32 v109, 0xffff0000, v94
	v_lshlrev_b32_e32 v110, 16, v95
	v_and_b32_e32 v111, 0xffff0000, v95
	ds_write_b128 v41, v[104:107]
	ds_write_b128 v41, v[108:111] offset:16
	s_or_b64 exec, exec, s[10:11]
	s_and_saveexec_b64 s[10:11], s[40:41]
	v_lshlrev_b32_e32 v112, 16, v96
	v_and_b32_e32 v113, 0xffff0000, v96
	v_lshlrev_b32_e32 v114, 16, v97
	v_and_b32_e32 v115, 0xffff0000, v97
	v_lshlrev_b32_e32 v116, 16, v98
	v_and_b32_e32 v117, 0xffff0000, v98
	v_lshlrev_b32_e32 v118, 16, v99
	v_and_b32_e32 v119, 0xffff0000, v99
	ds_write_b128 v42, v[112:115]
	ds_write_b128 v42, v[116:119] offset:16
	s_or_b64 exec, exec, s[10:11]
	s_and_saveexec_b64 s[10:11], s[42:43]
	v_lshlrev_b32_e32 v120, 16, v100
	v_and_b32_e32 v121, 0xffff0000, v100
	v_lshlrev_b32_e32 v122, 16, v101
	v_and_b32_e32 v123, 0xffff0000, v101
	v_lshlrev_b32_e32 v124, 16, v102
	v_and_b32_e32 v125, 0xffff0000, v102
	v_lshlrev_b32_e32 v126, 16, v103
	v_and_b32_e32 v127, 0xffff0000, v103
	ds_write_b128 v43, v[120:123]
	ds_write_b128 v43, v[124:127] offset:16
	s_or_b64 exec, exec, s[10:11]
	v_mov_b32_e32 v1, 0
	s_mov_b64 s[10:11], 0
	v_mov_b32_e32 v0, v25
	v_mov_b32_e32 v4, v16
	s_waitcnt lgkmcnt(0)
	s_barrier
